# attention loop v4: coarse waits, linear bias far from the diagonal, next-tile softmax in the PV part
# baseline (speedup 1.0000x reference)
; #define LAS __attribute__((address_space(3)))
; __device__ __forceinline__ void att_qk(const LAS unsigned char* Kb, const bf16x8 (&qf)[2][2], int nst, int j, int qpos, float slope2, int fr, int fq, f32x4 (&sc)[2][4]) {
;     constexpr int KSTR = 272;
; #pragma unroll
;     for (int st = 0; st < 4; ++st) {
;         if (st < nst) {
;             const float d0 = (float)(qpos - (64 * j + 16 * st + 4 * fq));
;             f32x4 s0;
; #pragma unroll
;             for (int e = 0; e < 4; ++e) s0[e] = -slope2 * __builtin_fabsf(d0 - (float)e) - 12.0f;
;             f32x4 s1 = s0;
; #pragma unroll
;             for (int ks = 0; ks < 2; ++ks) {
;                 const bf16x8 k0 = *(const LAS bf16x8*)(Kb + (16 * st + fr) * KSTR + (32 * ks + 8 * fq) * 2);
;                 const bf16x8 k1 = *(const LAS bf16x8*)(Kb + (16 * st + fr) * KSTR + (64 + 32 * ks + 8 * fq) * 2);
;                 s0 = __builtin_amdgcn_mfma_f32_16x16x32_bf16(k0, qf[0][ks], s0, 0, 0, 0);
;                 s1 = __builtin_amdgcn_mfma_f32_16x16x32_bf16(k1, qf[1][ks], s1, 0, 0, 0);
;             }
;             sc[0][st] = s0; sc[1][st] = s1;
;         }
;     }
; }
; __device__ __forceinline__ void att_pv(const LAS unsigned char* Vb, int nst, const f32x4 (&sc)[2][4], f32x4 (&O)[2][8], float& l0, float& l1, int fr, int fq) {
;     constexpr int VSTR = 144;
;     if (nst <= 0) return;
;     unsigned pw[2][4][2];
; #pragma unroll
;     for (int st = 0; st < 4; ++st) {
;         if (st < nst) {
;             float p0[4], p1[4];
; #pragma unroll
;             for (int e = 0; e < 4; ++e) { p0[e] = __builtin_amdgcn_exp2f(sc[0][st][e]); p1[e] = __builtin_amdgcn_exp2f(sc[1][st][e]); l0 += p0[e]; l1 += p1[e]; }
;             pw[0][st][0] = pk2(p0[0], p0[1]); pw[0][st][1] = pk2(p0[2], p0[3]); pw[1][st][0] = pk2(p1[0], p1[1]); pw[1][st][1] = pk2(p1[2], p1[3]);
; __device__ __forceinline__ void attn_phase(const Params& P, LAS unsigned char* lds, int tid, int wid, int lane) {
;     ...
;         __syncthreads();
;         ATT_LOADK(a, 0); ATT_LOADV(a, 0); ATT_WRITEK(a, 0); ATT_WRITEV(a, 0);
;         if (nt > 1) { ATT_LOADK(a, 1); ATT_WRITEK(a, 1); }
;         __syncthreads();
;         f32x4 scA[2][4], scB[2][4];
;         att_qk(lds, qf, ATT_NST(0), 0, qpos, slope2, fr, fq, scA);
;         for (int j = 0; j < nt; j += 2) {
;             if (j + 1 < nt) { if (j + 2 < nt) ATT_LOADK(a, j + 2); ATT_LOADV(a, j + 1); }
.LBB0_619:
	s_add_i32 s0, s6, 16
	s_lshl_b32 s0, s0, 10
	s_lshl_b32 s1, s34, 1
	s_add_u32 s22, s10, s0
	s_addc_u32 s23, s11, 0
	s_add_u32 s22, s22, s1
	s_addc_u32 s23, s23, 0
	s_bfe_u32 s0, s17, 0x50003
	s_mul_i32 s0, s0, 0x84000
	s_add_u32 s24, s86, 0xb700000
	s_addc_u32 s25, s87, 0
	s_add_u32 s24, s24, s0
	s_addc_u32 s25, s25, 0
	s_mov_b32 s18, 0xc6ea6000
	s_xor_b32 s19, s20, 0x80000000
	s_movk_i32 s46, 0x1080
	s_mov_b32 s4, 0
	v_and_b32_e32 v46, 3, v209
	v_lshlrev_b32_e32 v46, 4, v46
	v_mad_u32_u24 v46, v240, s46, v46
	v_add_u32_e32 v47, s31, v249
	v_add_u32_e32 v47, 16, v47
	v_cvt_f32_i32_e32 v47, v47
	v_add_f32_e32 v47, 0xc2800000, v47
	v_mov_b32_e32 v236, 0
	v_mov_b32_e32 v237, 0
	v_cvt_f32_u32_e32 v223, v208
	v_mul_f32_e32 v223, s20, v223
	s_nop 1
	v_readlane_b32 s6, v223, 1
	v_readlane_b32 s20, v223, 2
	v_readlane_b32 s21, v223, 3
	v_readlane_b32 s35, v223, 16
	v_readlane_b32 s38, v223, 17
	v_readlane_b32 s39, v223, 18
	v_readlane_b32 s40, v223, 19
	v_readlane_b32 s41, v223, 32
	v_readlane_b32 s42, v223, 33
	v_readlane_b32 s48, v223, 34
	v_readlane_b32 s49, v223, 35
	v_readlane_b32 s98, v223, 48
	v_readlane_b32 s99, v223, 49
	v_readlane_b32 s100, v223, 50
	v_readlane_b32 s101, v223, 51
	s_mov_b32 s5, 1
	s_cmp_le_u32 s5, s37
	s_cselect_b32 s45, s16, s18
	s_add_i32 s0, s37, 1
	s_cmp_le_u32 s5, s0
	s_cselect_b32 s43, s16, s18
	v_mov_b32_e32 v4, s43
	v_fma_f32 v48, |v47|, s19, v4
	v_subrev_f32_e32 v49, 0x3f800000, v47
	v_fma_f32 v49, |v49|, s19, v4
	v_subrev_f32_e32 v50, 0x40000000, v47
	v_fma_f32 v50, |v50|, s19, v4
	v_subrev_f32_e32 v51, 0x40400000, v47
	v_fma_f32 v51, |v51|, s19, v4
	v_mov_b32_e32 v4, s45
	v_subrev_f32_e32 v52, 0x41800000, v47
	v_fma_f32 v52, |v52|, s19, v4
	v_subrev_f32_e32 v53, 0x41880000, v47
	v_fma_f32 v53, |v53|, s19, v4
	v_subrev_f32_e32 v54, 0x41900000, v47
	v_fma_f32 v54, |v54|, s19, v4
	v_subrev_f32_e32 v55, 0x41980000, v47
	v_fma_f32 v55, |v55|, s19, v4
	v_subrev_f32_e32 v56, 0x42000000, v47
	v_fma_f32 v56, |v56|, s19, v4
	v_subrev_f32_e32 v57, 0x42040000, v47
	v_fma_f32 v57, |v57|, s19, v4
	v_subrev_f32_e32 v58, 0x42080000, v47
	v_fma_f32 v58, |v58|, s19, v4
	v_subrev_f32_e32 v59, 0x420c0000, v47
	v_fma_f32 v59, |v59|, s19, v4
	v_subrev_f32_e32 v60, 0x42400000, v47
	v_fma_f32 v60, |v60|, s19, v4
	v_subrev_f32_e32 v61, 0x42440000, v47
	v_fma_f32 v61, |v61|, s19, v4
	v_subrev_f32_e32 v62, 0x42480000, v47
	v_fma_f32 v62, |v62|, s19, v4
	v_subrev_f32_e32 v63, 0x424c0000, v47
	v_fma_f32 v63, |v63|, s19, v4
	v_add_f32_e32 v47, 0xc2800000, v47
	s_sub_i32 s1, s36, 1
	s_add_i32 s0, s4, 2
	s_min_u32 s0, s0, s1
	s_add_i32 s5, s4, 1
	s_min_u32 s5, s5, s1
	s_lshl_b32 s0, s0, 6
	s_lshl_b32 s5, s5, 7
	v_add_u32_e32 v223, s0, v243
	v_min_u32_e32 v223, 0x7ff, v223
	v_lshl_add_u32 v223, v223, 10, v224
	s_add_u32 s26, s24, s5
	s_addc_u32 s27, s25, 0
	global_load_dwordx4 v[84:87], v223, s[22:23]
	global_load_dwordx4 v[88:91], v223, s[22:23] offset:128
	global_load_dwordx4 v[92:95], v46, s[26:27]
	global_load_dwordx4 v[96:99], v46, s[26:27] offset:64
	v_exp_f32_e32 v152, v152
	v_exp_f32_e32 v153, v153
	v_exp_f32_e32 v154, v154
	v_exp_f32_e32 v155, v155
	v_exp_f32_e32 v156, v156
	v_exp_f32_e32 v157, v157
	v_exp_f32_e32 v158, v158
	v_exp_f32_e32 v159, v159
	v_exp_f32_e32 v168, v168
	v_exp_f32_e32 v169, v169
	v_exp_f32_e32 v170, v170
	v_exp_f32_e32 v171, v171
	v_exp_f32_e32 v172, v172
	v_exp_f32_e32 v173, v173
	v_exp_f32_e32 v174, v174
	v_exp_f32_e32 v175, v175
	v_cvt_pk_bf16_f32 v38, v152, v153
	v_cvt_pk_bf16_f32 v39, v154, v155
	v_cvt_pk_bf16_f32 v42, v156, v157
	v_cvt_pk_bf16_f32 v43, v158, v159
	v_pk_add_f32 v[234:235], v[234:235], v[152:153]
	v_pk_add_f32 v[234:235], v[234:235], v[154:155]
	v_pk_add_f32 v[236:237], v[236:237], v[156:157]
	v_pk_add_f32 v[236:237], v[236:237], v[158:159]
	v_cvt_pk_bf16_f32 v40, v168, v169
	v_cvt_pk_bf16_f32 v41, v170, v171
	v_cvt_pk_bf16_f32 v44, v172, v173
	v_cvt_pk_bf16_f32 v45, v174, v175
	v_pk_add_f32 v[234:235], v[234:235], v[168:169]
	v_pk_add_f32 v[234:235], v[234:235], v[170:171]
	v_pk_add_f32 v[236:237], v[236:237], v[172:173]
	v_pk_add_f32 v[236:237], v[236:237], v[174:175]

; __device__ __forceinline__ void att_qk(const LAS unsigned char* Kb, const bf16x8 (&qf)[2][2], int nst, int j, int qpos, float slope2, int fr, int fq, f32x4 (&sc)[2][4]) {
;     constexpr int KSTR = 272;
; #pragma unroll
;     for (int st = 0; st < 4; ++st) {
;         if (st < nst) {
;             const float d0 = (float)(qpos - (64 * j + 16 * st + 4 * fq));
;             f32x4 s0;
; #pragma unroll
;             for (int e = 0; e < 4; ++e) s0[e] = -slope2 * __builtin_fabsf(d0 - (float)e) - 12.0f;
;             f32x4 s1 = s0;
; #pragma unroll
;             for (int ks = 0; ks < 2; ++ks) {
;                 const bf16x8 k0 = *(const LAS bf16x8*)(Kb + (16 * st + fr) * KSTR + (32 * ks + 8 * fq) * 2);
;                 const bf16x8 k1 = *(const LAS bf16x8*)(Kb + (16 * st + fr) * KSTR + (64 + 32 * ks + 8 * fq) * 2);
;                 s0 = __builtin_amdgcn_mfma_f32_16x16x32_bf16(k0, qf[0][ks], s0, 0, 0, 0);
;                 s1 = __builtin_amdgcn_mfma_f32_16x16x32_bf16(k1, qf[1][ks], s1, 0, 0, 0);
;             }
;             sc[0][st] = s0; sc[1][st] = s1;
;         }
;     }
; }
; __device__ __forceinline__ void att_pv(const LAS unsigned char* Vb, int nst, const f32x4 (&sc)[2][4], f32x4 (&O)[2][8], float& l0, float& l1, int fr, int fq) {
;     constexpr int VSTR = 144;
;     if (nst <= 0) return;
;     unsigned pw[2][4][2];
; #pragma unroll
;     for (int st = 0; st < 4; ++st) {
;         if (st < nst) {
;             float p0[4], p1[4];
; #pragma unroll
;             for (int e = 0; e < 4; ++e) { p0[e] = __builtin_amdgcn_exp2f(sc[0][st][e]); p1[e] = __builtin_amdgcn_exp2f(sc[1][st][e]); l0 += p0[e]; l1 += p1[e]; }
;             pw[0][st][0] = pk2(p0[0], p0[1]); pw[0][st][1] = pk2(p0[2], p0[3]); pw[1][st][0] = pk2(p1[0], p1[1]); pw[1][st][1] = pk2(p1[2], p1[3]);
;         } else { pw[0][st][0] = 0u; pw[0][st][1] = 0u; pw[1][st][0] = 0u; pw[1][st][1] = 0u; }
;     }
; #pragma unroll
;     for (int ks2 = 0; ks2 < 2; ++ks2) {
;         if (ks2 == 0 || nst == 4) {
;             const u32x4 a0 = (u32x4){pw[0][2 * ks2][0], pw[0][2 * ks2][1], pw[0][2 * ks2 + 1][0], pw[0][2 * ks2 + 1][1]};
;             const u32x4 a1 = (u32x4){pw[1][2 * ks2][0], pw[1][2 * ks2][1], pw[1][2 * ks2 + 1][0], pw[1][2 * ks2 + 1][1]};
;             const bf16x8 pf0 = __builtin_bit_cast(bf16x8, a0), pf1 = __builtin_bit_cast(bf16x8, a1);
; #pragma unroll
.Latt_it_e:
	ds_read_b128 v[6:9], v253 offset:17536
	ds_read_b128 v[10:13], v253 offset:17408
	ds_read_b128 v[14:17], v253 offset:21888
	ds_read_b128 v[18:21], v253 offset:21760
	ds_read_b128 v[22:25], v253 offset:26240
	ds_read_b128 v[26:29], v253 offset:26112
	ds_read_b128 v[30:33], v253 offset:30592
	ds_read_b128 v[34:37], v253 offset:30464
	v_exp_f32_e32 v192, v192
	v_exp_f32_e32 v193, v193
	v_exp_f32_e32 v194, v194
	v_exp_f32_e32 v195, v195
	v_exp_f32_e32 v196, v196
	v_exp_f32_e32 v197, v197
	v_exp_f32_e32 v198, v198
	v_exp_f32_e32 v199, v199
	s_waitcnt lgkmcnt(6)
	v_mfma_f32_16x16x32_bf16 v[64:67], v[6:9], v[112:115], v[48:51]
	v_mfma_f32_16x16x32_bf16 v[48:51], v[10:13], v[80:83], v[48:51]
	ds_read_b128 v[6:9], v253 offset:17600
	ds_read_b128 v[10:13], v253 offset:17472
	v_exp_f32_e32 v200, v200
	v_exp_f32_e32 v201, v201
	v_exp_f32_e32 v202, v202
	s_waitcnt lgkmcnt(6)
	v_mfma_f32_16x16x32_bf16 v[68:71], v[14:17], v[112:115], v[52:55]
	v_mfma_f32_16x16x32_bf16 v[52:55], v[18:21], v[80:83], v[52:55]
	ds_read_b128 v[14:17], v253 offset:21952
	ds_read_b128 v[18:21], v253 offset:21824
	v_exp_f32_e32 v203, v203
	v_exp_f32_e32 v204, v204
	v_exp_f32_e32 v205, v205
	s_waitcnt lgkmcnt(6)
	v_mfma_f32_16x16x32_bf16 v[72:75], v[22:25], v[112:115], v[56:59]
	v_mfma_f32_16x16x32_bf16 v[56:59], v[26:29], v[80:83], v[56:59]
	ds_read_b128 v[22:25], v253 offset:26304
	ds_read_b128 v[26:29], v253 offset:26176
	v_exp_f32_e32 v206, v206
	v_exp_f32_e32 v207, v207
	v_cvt_pk_bf16_f32 v0, v192, v193
	s_waitcnt lgkmcnt(6)
	v_mfma_f32_16x16x32_bf16 v[76:79], v[30:33], v[112:115], v[60:63]
	v_mfma_f32_16x16x32_bf16 v[60:63], v[34:37], v[80:83], v[60:63]
	ds_read_b128 v[30:33], v253 offset:30656
	ds_read_b128 v[34:37], v253 offset:30528
	v_cvt_pk_bf16_f32 v1, v194, v195
	v_cvt_pk_bf16_f32 v230, v196, v197
	v_cvt_pk_bf16_f32 v231, v198, v199
	s_waitcnt lgkmcnt(6)
	v_mfma_f32_16x16x32_bf16 v[64:67], v[6:9], v[128:131], v[64:67]
	v_mfma_f32_16x16x32_bf16 v[48:51], v[10:13], v[104:107], v[48:51]
	ds_read_b64 v[6:7], v245 offset:34816
	ds_read_b64 v[8:9], v245 offset:34848
	ds_read_b64 v[10:11], v245 offset:37120
	ds_read_b64 v[12:13], v245 offset:37152
	v_pk_add_f32 v[234:235], v[234:235], v[192:193]
	v_pk_add_f32 v[234:235], v[234:235], v[194:195]
	v_pk_add_f32 v[236:237], v[236:237], v[196:197]
	s_waitcnt lgkmcnt(8)
	v_mfma_f32_16x16x32_bf16 v[68:71], v[14:17], v[128:131], v[68:71]
	v_mfma_f32_16x16x32_bf16 v[52:55], v[18:21], v[104:107], v[52:55]
	ds_read_b64 v[14:15], v245 offset:39424
	ds_read_b64 v[16:17], v245 offset:39456
	ds_read_b64 v[18:19], v245 offset:41728
	ds_read_b64 v[20:21], v245 offset:41760
	v_pk_add_f32 v[236:237], v[236:237], v[198:199]
	v_cvt_pk_bf16_f32 v2, v200, v201
	v_cvt_pk_bf16_f32 v3, v202, v203
	s_waitcnt lgkmcnt(10)
	v_mfma_f32_16x16x32_bf16 v[72:75], v[22:25], v[128:131], v[72:75]
	v_mfma_f32_16x16x32_bf16 v[56:59], v[26:29], v[104:107], v[56:59]
	ds_read_b64 v[22:23], v245 offset:44032
	ds_read_b64 v[24:25], v245 offset:44064
	ds_read_b64 v[26:27], v245 offset:46336
	ds_read_b64 v[28:29], v245 offset:46368
	v_cvt_pk_bf16_f32 v232, v204, v205
	v_cvt_pk_bf16_f32 v233, v206, v207
	v_pk_add_f32 v[234:235], v[234:235], v[200:201]
	s_waitcnt lgkmcnt(12)
	v_mfma_f32_16x16x32_bf16 v[76:79], v[30:33], v[128:131], v[76:79]
	v_mfma_f32_16x16x32_bf16 v[60:63], v[34:37], v[104:107], v[60:63]
	ds_read_b64 v[30:31], v245 offset:48640
	ds_read_b64 v[32:33], v245 offset:48672
	ds_read_b64 v[34:35], v245 offset:50944
	ds_read_b64 v[36:37], v245 offset:50976
	v_pk_add_f32 v[234:235], v[234:235], v[202:203]
	v_pk_add_f32 v[236:237], v[236:237], v[204:205]
	v_pk_add_f32 v[236:237], v[236:237], v[206:207]
	s_add_i32 s5, s4, 2
	s_cmp_lt_u32 s5, s37
	s_cbranch_scc1 .Latt_lin_e
	s_cmp_le_u32 s5, s37
	s_cselect_b32 s45, s16, s18
	s_add_i32 s0, s37, 1
	s_cmp_le_u32 s5, s0
	s_cselect_b32 s43, s16, s18
	s_waitcnt lgkmcnt(12)
	v_mfma_f32_16x16x32_bf16 v[184:187], v[6:9], v[38:41], v[184:187]
	v_mfma_f32_16x16x32_bf16 v[188:191], v[6:9], v[42:45], v[188:191]
	v_mfma_f32_16x16x32_bf16 v[180:183], v[10:13], v[38:41], v[180:183]
	v_mfma_f32_16x16x32_bf16 v[176:179], v[10:13], v[42:45], v[176:179]
	ds_read_b64 v[6:7], v245 offset:34880
	ds_read_b64 v[8:9], v245 offset:34912
	ds_read_b64 v[10:11], v245 offset:37184
	ds_read_b64 v[12:13], v245 offset:37216
	v_mov_b32_e32 v4, s43
	v_fma_f32 v152, |v47|, s19, v4
	v_subrev_f32_e32 v153, 0x3f800000, v47
	v_fma_f32 v153, |v153|, s19, v4
	v_subrev_f32_e32 v154, 0x40000000, v47
	v_fma_f32 v154, |v154|, s19, v4
	v_subrev_f32_e32 v155, 0x40400000, v47
	v_fma_f32 v155, |v155|, s19, v4
	v_mov_b32_e32 v4, s45
	s_waitcnt lgkmcnt(12)
	v_mfma_f32_16x16x32_bf16 v[164:167], v[14:17], v[38:41], v[164:167]
	v_mfma_f32_16x16x32_bf16 v[160:163], v[14:17], v[42:45], v[160:163]
	v_mfma_f32_16x16x32_bf16 v[148:151], v[18:21], v[38:41], v[148:151]
	v_mfma_f32_16x16x32_bf16 v[144:147], v[18:21], v[42:45], v[144:147]
	ds_read_b64 v[14:15], v245 offset:39488
	ds_read_b64 v[16:17], v245 offset:39520
	ds_read_b64 v[18:19], v245 offset:41792
	ds_read_b64 v[20:21], v245 offset:41824
	v_subrev_f32_e32 v168, 0x41800000, v47
	v_fma_f32 v168, |v168|, s19, v4
	v_subrev_f32_e32 v169, 0x41880000, v47
	v_fma_f32 v169, |v169|, s19, v4
	v_subrev_f32_e32 v170, 0x41900000, v47
	v_fma_f32 v170, |v170|, s19, v4
	v_subrev_f32_e32 v171, 0x41980000, v47
	v_fma_f32 v171, |v171|, s19, v4
	v_subrev_f32_e32 v192, 0x42000000, v47
	s_waitcnt lgkmcnt(12)
	v_mfma_f32_16x16x32_bf16 v[140:143], v[22:25], v[38:41], v[140:143]
	v_mfma_f32_16x16x32_bf16 v[136:139], v[22:25], v[42:45], v[136:139]
	v_mfma_f32_16x16x32_bf16 v[132:135], v[26:29], v[38:41], v[132:135]
	v_mfma_f32_16x16x32_bf16 v[124:127], v[26:29], v[42:45], v[124:127]
	ds_read_b64 v[22:23], v245 offset:44096
	ds_read_b64 v[24:25], v245 offset:44128
	ds_read_b64 v[26:27], v245 offset:46400
	ds_read_b64 v[28:29], v245 offset:46432
	v_fma_f32 v192, |v192|, s19, v4
	v_subrev_f32_e32 v193, 0x42040000, v47
	v_fma_f32 v193, |v193|, s19, v4
	v_subrev_f32_e32 v194, 0x42080000, v47
	v_fma_f32 v194, |v194|, s19, v4
	v_subrev_f32_e32 v195, 0x420c0000, v47
	v_fma_f32 v195, |v195|, s19, v4
	v_subrev_f32_e32 v200, 0x42400000, v47
	s_waitcnt lgkmcnt(12)
	v_mfma_f32_16x16x32_bf16 v[120:123], v[30:33], v[38:41], v[120:123]
	v_mfma_f32_16x16x32_bf16 v[116:119], v[30:33], v[42:45], v[116:119]
	v_mfma_f32_16x16x32_bf16 v[108:111], v[34:37], v[38:41], v[108:111]
	v_mfma_f32_16x16x32_bf16 v[100:103], v[34:37], v[42:45], v[100:103]
	ds_read_b64 v[30:31], v245 offset:48704
	ds_read_b64 v[32:33], v245 offset:48736
	ds_read_b64 v[34:35], v245 offset:51008
	ds_read_b64 v[36:37], v245 offset:51040
	v_fma_f32 v200, |v200|, s19, v4
	v_subrev_f32_e32 v201, 0x42440000, v47
	v_fma_f32 v201, |v201|, s19, v4
	v_subrev_f32_e32 v202, 0x42480000, v47
	v_fma_f32 v202, |v202|, s19, v4
	v_subrev_f32_e32 v203, 0x424c0000, v47
	v_fma_f32 v203, |v203|, s19, v4
	v_add_f32_e32 v47, 0xc2800000, v47
	s_branch .Latt_c_e
; __device__ __forceinline__ void att_qk(const LAS unsigned char* Kb, const bf16x8 (&qf)[2][2], int nst, int j, int qpos, float slope2, int fr, int fq, f32x4 (&sc)[2][4]) {
;     constexpr int KSTR = 272;
; #pragma unroll
;     for (int st = 0; st < 4; ++st) {
;         if (st < nst) {
;             const float d0 = (float)(qpos - (64 * j + 16 * st + 4 * fq));
;             f32x4 s0;
; #pragma unroll
;             for (int e = 0; e < 4; ++e) s0[e] = -slope2 * __builtin_fabsf(d0 - (float)e) - 12.0f;
;             f32x4 s1 = s0;
; #pragma unroll
;             for (int ks = 0; ks < 2; ++ks) {
;                 const bf16x8 k0 = *(const LAS bf16x8*)(Kb + (16 * st + fr) * KSTR + (32 * ks + 8 * fq) * 2);
;                 const bf16x8 k1 = *(const LAS bf16x8*)(Kb + (16 * st + fr) * KSTR + (64 + 32 * ks + 8 * fq) * 2);
;                 s0 = __builtin_amdgcn_mfma_f32_16x16x32_bf16(k0, qf[0][ks], s0, 0, 0, 0);
;                 s1 = __builtin_amdgcn_mfma_f32_16x16x32_bf16(k1, qf[1][ks], s1, 0, 0, 0);
;             }
;             sc[0][st] = s0; sc[1][st] = s1;
;         }
;     }
; }
; __device__ __forceinline__ void att_pv(const LAS unsigned char* Vb, int nst, const f32x4 (&sc)[2][4], f32x4 (&O)[2][8], float& l0, float& l1, int fr, int fq) {
;     constexpr int VSTR = 144;
;     if (nst <= 0) return;
;     unsigned pw[2][4][2];
; #pragma unroll
;     for (int st = 0; st < 4; ++st) {
;         if (st < nst) {
;             float p0[4], p1[4];
; #pragma unroll
;             for (int e = 0; e < 4; ++e) { p0[e] = __builtin_amdgcn_exp2f(sc[0][st][e]); p1[e] = __builtin_amdgcn_exp2f(sc[1][st][e]); l0 += p0[e]; l1 += p1[e]; }
;             pw[0][st][0] = pk2(p0[0], p0[1]); pw[0][st][1] = pk2(p0[2], p0[3]); pw[1][st][0] = pk2(p1[0], p1[1]); pw[1][st][1] = pk2(p1[2], p1[3]);
;         } else { pw[0][st][0] = 0u; pw[0][st][1] = 0u; pw[1][st][0] = 0u; pw[1][st][1] = 0u; }
;     }
; #pragma unroll
;     for (int ks2 = 0; ks2 < 2; ++ks2) {
;         if (ks2 == 0 || nst == 4) {
;             const u32x4 a0 = (u32x4){pw[0][2 * ks2][0], pw[0][2 * ks2][1], pw[0][2 * ks2 + 1][0], pw[0][2 * ks2 + 1][1]};
;             const u32x4 a1 = (u32x4){pw[1][2 * ks2][0], pw[1][2 * ks2][1], pw[1][2 * ks2 + 1][0], pw[1][2 * ks2 + 1][1]};
;             const bf16x8 pf0 = __builtin_bit_cast(bf16x8, a0), pf1 = __builtin_bit_cast(bf16x8, a1);
; #pragma unroll
.Latt_lin_e:
	s_waitcnt lgkmcnt(12)
	v_mfma_f32_16x16x32_bf16 v[184:187], v[6:9], v[38:41], v[184:187]
	v_mfma_f32_16x16x32_bf16 v[188:191], v[6:9], v[42:45], v[188:191]
	v_mfma_f32_16x16x32_bf16 v[180:183], v[10:13], v[38:41], v[180:183]
	v_mfma_f32_16x16x32_bf16 v[176:179], v[10:13], v[42:45], v[176:179]
	ds_read_b64 v[6:7], v245 offset:34880
	ds_read_b64 v[8:9], v245 offset:34912
	ds_read_b64 v[10:11], v245 offset:37184
	ds_read_b64 v[12:13], v245 offset:37216
	v_mov_b32_e32 v4, s16
	v_fma_f32 v4, v47, s19, v4
	v_mov_b32_e32 v152, v4
	v_add_f32_e32 v153, s6, v4
	v_add_f32_e32 v154, s20, v4
	s_waitcnt lgkmcnt(12)
	v_mfma_f32_16x16x32_bf16 v[164:167], v[14:17], v[38:41], v[164:167]
	v_mfma_f32_16x16x32_bf16 v[160:163], v[14:17], v[42:45], v[160:163]
	v_mfma_f32_16x16x32_bf16 v[148:151], v[18:21], v[38:41], v[148:151]
	v_mfma_f32_16x16x32_bf16 v[144:147], v[18:21], v[42:45], v[144:147]
	ds_read_b64 v[14:15], v245 offset:39488
	ds_read_b64 v[16:17], v245 offset:39520
	ds_read_b64 v[18:19], v245 offset:41792
	ds_read_b64 v[20:21], v245 offset:41824
	v_add_f32_e32 v155, s21, v4
	v_add_f32_e32 v168, s35, v4
	v_add_f32_e32 v169, s38, v4
	v_add_f32_e32 v170, s39, v4
	v_add_f32_e32 v171, s40, v4
	s_waitcnt lgkmcnt(12)
	v_mfma_f32_16x16x32_bf16 v[140:143], v[22:25], v[38:41], v[140:143]
	v_mfma_f32_16x16x32_bf16 v[136:139], v[22:25], v[42:45], v[136:139]
	v_mfma_f32_16x16x32_bf16 v[132:135], v[26:29], v[38:41], v[132:135]
	v_mfma_f32_16x16x32_bf16 v[124:127], v[26:29], v[42:45], v[124:127]
	ds_read_b64 v[22:23], v245 offset:44096
	ds_read_b64 v[24:25], v245 offset:44128
	ds_read_b64 v[26:27], v245 offset:46400
	ds_read_b64 v[28:29], v245 offset:46432
	v_add_f32_e32 v192, s41, v4
	v_add_f32_e32 v193, s42, v4
	v_add_f32_e32 v194, s48, v4
	v_add_f32_e32 v195, s49, v4
	v_add_f32_e32 v200, s98, v4
	s_waitcnt lgkmcnt(12)
	v_mfma_f32_16x16x32_bf16 v[120:123], v[30:33], v[38:41], v[120:123]
	v_mfma_f32_16x16x32_bf16 v[116:119], v[30:33], v[42:45], v[116:119]
	v_mfma_f32_16x16x32_bf16 v[108:111], v[34:37], v[38:41], v[108:111]
	v_mfma_f32_16x16x32_bf16 v[100:103], v[34:37], v[42:45], v[100:103]
	ds_read_b64 v[30:31], v245 offset:48704
	ds_read_b64 v[32:33], v245 offset:48736
	ds_read_b64 v[34:35], v245 offset:51008
	ds_read_b64 v[36:37], v245 offset:51040
	v_add_f32_e32 v201, s99, v4
	v_add_f32_e32 v202, s100, v4
	v_add_f32_e32 v203, s101, v4
	v_add_f32_e32 v47, 0xc2800000, v47
.Latt_c_e:
	s_waitcnt vmcnt(0)
	ds_write_b128 v251, v[84:87] offset:0
	ds_write_b128 v251, v[88:91] offset:128
	ds_write_b128 v252, v[92:95] offset:53248
	ds_write_b128 v252, v[96:99] offset:53312
	s_sub_i32 s1, s36, 1
	s_add_i32 s0, s4, 3
	s_min_u32 s0, s0, s1
	s_add_i32 s5, s4, 2
	s_min_u32 s5, s5, s1
	s_lshl_b32 s0, s0, 6
	s_lshl_b32 s5, s5, 7
	v_add_u32_e32 v223, s0, v243
	v_min_u32_e32 v223, 0x7ff, v223
	v_lshl_add_u32 v223, v223, 10, v224
	s_add_u32 s26, s24, s5
	s_addc_u32 s27, s25, 0
	global_load_dwordx4 v[84:87], v223, s[22:23]
	global_load_dwordx4 v[88:91], v223, s[22:23] offset:128
	global_load_dwordx4 v[92:95], v46, s[26:27]
	global_load_dwordx4 v[96:99], v46, s[26:27] offset:64
	s_waitcnt lgkmcnt(15)
	v_mfma_f32_16x16x32_bf16 v[184:187], v[6:9], v[0:3], v[184:187]
	v_mfma_f32_16x16x32_bf16 v[188:191], v[6:9], v[230:233], v[188:191]
	v_mfma_f32_16x16x32_bf16 v[180:183], v[10:13], v[0:3], v[180:183]
	v_mfma_f32_16x16x32_bf16 v[176:179], v[10:13], v[230:233], v[176:179]
	v_exp_f32_e32 v48, v48
	v_exp_f32_e32 v49, v49
	v_exp_f32_e32 v50, v50
	v_exp_f32_e32 v51, v51
	v_exp_f32_e32 v64, v64
	v_exp_f32_e32 v65, v65
	v_exp_f32_e32 v66, v66
	v_exp_f32_e32 v67, v67
	s_waitcnt lgkmcnt(12)
	v_mfma_f32_16x16x32_bf16 v[164:167], v[14:17], v[0:3], v[164:167]
	v_mfma_f32_16x16x32_bf16 v[160:163], v[14:17], v[230:233], v[160:163]
	v_mfma_f32_16x16x32_bf16 v[148:151], v[18:21], v[0:3], v[148:151]
	v_mfma_f32_16x16x32_bf16 v[144:147], v[18:21], v[230:233], v[144:147]
	v_exp_f32_e32 v52, v52
	v_exp_f32_e32 v53, v53
	v_exp_f32_e32 v54, v54
	v_exp_f32_e32 v55, v55
	v_exp_f32_e32 v68, v68
	v_exp_f32_e32 v69, v69
	v_exp_f32_e32 v70, v70
	v_exp_f32_e32 v71, v71
	s_waitcnt lgkmcnt(8)
	v_mfma_f32_16x16x32_bf16 v[140:143], v[22:25], v[0:3], v[140:143]
	v_mfma_f32_16x16x32_bf16 v[136:139], v[22:25], v[230:233], v[136:139]
	v_mfma_f32_16x16x32_bf16 v[132:135], v[26:29], v[0:3], v[132:135]
	v_mfma_f32_16x16x32_bf16 v[124:127], v[26:29], v[230:233], v[124:127]
	v_cvt_pk_bf16_f32 v38, v48, v49
	v_cvt_pk_bf16_f32 v39, v50, v51
	v_cvt_pk_bf16_f32 v42, v64, v65
	v_cvt_pk_bf16_f32 v43, v66, v67
	v_pk_add_f32 v[234:235], v[234:235], v[48:49]
	v_pk_add_f32 v[234:235], v[234:235], v[50:51]
	v_pk_add_f32 v[236:237], v[236:237], v[64:65]
	v_pk_add_f32 v[236:237], v[236:237], v[66:67]
	s_waitcnt lgkmcnt(4)
	v_mfma_f32_16x16x32_bf16 v[120:123], v[30:33], v[0:3], v[120:123]
	v_mfma_f32_16x16x32_bf16 v[116:119], v[30:33], v[230:233], v[116:119]
	v_mfma_f32_16x16x32_bf16 v[108:111], v[34:37], v[0:3], v[108:111]
	v_mfma_f32_16x16x32_bf16 v[100:103], v[34:37], v[230:233], v[100:103]
	v_cvt_pk_bf16_f32 v40, v52, v53
	v_cvt_pk_bf16_f32 v41, v54, v55
	v_cvt_pk_bf16_f32 v44, v68, v69
	v_cvt_pk_bf16_f32 v45, v70, v71
	v_pk_add_f32 v[234:235], v[234:235], v[52:53]
	v_pk_add_f32 v[234:235], v[234:235], v[54:55]
	v_pk_add_f32 v[236:237], v[236:237], v[68:69]
	v_pk_add_f32 v[236:237], v[236:237], v[70:71]
	s_waitcnt lgkmcnt(0)
	s_barrier
	s_add_i32 s4, s4, 1
; __device__ __forceinline__ void att_qk(const LAS unsigned char* Kb, const bf16x8 (&qf)[2][2], int nst, int j, int qpos, float slope2, int fr, int fq, f32x4 (&sc)[2][4]) {
;     constexpr int KSTR = 272;
; #pragma unroll
;     for (int st = 0; st < 4; ++st) {
;         if (st < nst) {
;             const float d0 = (float)(qpos - (64 * j + 16 * st + 4 * fq));
;             f32x4 s0;
; #pragma unroll
;             for (int e = 0; e < 4; ++e) s0[e] = -slope2 * __builtin_fabsf(d0 - (float)e) - 12.0f;
;             f32x4 s1 = s0;
; #pragma unroll
;             for (int ks = 0; ks < 2; ++ks) {
;                 const bf16x8 k0 = *(const LAS bf16x8*)(Kb + (16 * st + fr) * KSTR + (32 * ks + 8 * fq) * 2);
;                 const bf16x8 k1 = *(const LAS bf16x8*)(Kb + (16 * st + fr) * KSTR + (64 + 32 * ks + 8 * fq) * 2);
;                 s0 = __builtin_amdgcn_mfma_f32_16x16x32_bf16(k0, qf[0][ks], s0, 0, 0, 0);
;                 s1 = __builtin_amdgcn_mfma_f32_16x16x32_bf16(k1, qf[1][ks], s1, 0, 0, 0);
;             }
;             sc[0][st] = s0; sc[1][st] = s1;
;         }
;     }
; }
; __device__ __forceinline__ void att_pv(const LAS unsigned char* Vb, int nst, const f32x4 (&sc)[2][4], f32x4 (&O)[2][8], float& l0, float& l1, int fr, int fq) {
;     constexpr int VSTR = 144;
;     if (nst <= 0) return;
;     unsigned pw[2][4][2];
; #pragma unroll
;     for (int st = 0; st < 4; ++st) {
;         if (st < nst) {
;             float p0[4], p1[4];
; #pragma unroll
;             for (int e = 0; e < 4; ++e) { p0[e] = __builtin_amdgcn_exp2f(sc[0][st][e]); p1[e] = __builtin_amdgcn_exp2f(sc[1][st][e]); l0 += p0[e]; l1 += p1[e]; }
;             pw[0][st][0] = pk2(p0[0], p0[1]); pw[0][st][1] = pk2(p0[2], p0[3]); pw[1][st][0] = pk2(p1[0], p1[1]); pw[1][st][1] = pk2(p1[2], p1[3]);
;         } else { pw[0][st][0] = 0u; pw[0][st][1] = 0u; pw[1][st][0] = 0u; pw[1][st][1] = 0u; }
;     }
; #pragma unroll
;     for (int ks2 = 0; ks2 < 2; ++ks2) {
;         if (ks2 == 0 || nst == 4) {
;             const u32x4 a0 = (u32x4){pw[0][2 * ks2][0], pw[0][2 * ks2][1], pw[0][2 * ks2 + 1][0], pw[0][2 * ks2 + 1][1]};
;             const u32x4 a1 = (u32x4){pw[1][2 * ks2][0], pw[1][2 * ks2][1], pw[1][2 * ks2 + 1][0], pw[1][2 * ks2 + 1][1]};
;             const bf16x8 pf0 = __builtin_bit_cast(bf16x8, a0), pf1 = __builtin_bit_cast(bf16x8, a1);
; #pragma unroll
.Latt_it_o:
	ds_read_b128 v[6:9], v253 offset:128
	ds_read_b128 v[10:13], v253 offset:0
	ds_read_b128 v[14:17], v253 offset:4480
	ds_read_b128 v[18:21], v253 offset:4352
	ds_read_b128 v[22:25], v253 offset:8832
	ds_read_b128 v[26:29], v253 offset:8704
	ds_read_b128 v[30:33], v253 offset:13184
	ds_read_b128 v[34:37], v253 offset:13056
	v_exp_f32_e32 v56, v56
	v_exp_f32_e32 v57, v57
	v_exp_f32_e32 v58, v58
	v_exp_f32_e32 v59, v59
	v_exp_f32_e32 v72, v72
	v_exp_f32_e32 v73, v73
	v_exp_f32_e32 v74, v74
	v_exp_f32_e32 v75, v75
	s_waitcnt lgkmcnt(6)
	v_mfma_f32_16x16x32_bf16 v[156:159], v[6:9], v[112:115], v[152:155]
	v_mfma_f32_16x16x32_bf16 v[152:155], v[10:13], v[80:83], v[152:155]
	ds_read_b128 v[6:9], v253 offset:192
	ds_read_b128 v[10:13], v253 offset:64
	v_exp_f32_e32 v60, v60
	v_exp_f32_e32 v61, v61
	v_exp_f32_e32 v62, v62
	s_waitcnt lgkmcnt(6)
	v_mfma_f32_16x16x32_bf16 v[172:175], v[14:17], v[112:115], v[168:171]
	v_mfma_f32_16x16x32_bf16 v[168:171], v[18:21], v[80:83], v[168:171]
	ds_read_b128 v[14:17], v253 offset:4544
	ds_read_b128 v[18:21], v253 offset:4416
	v_exp_f32_e32 v63, v63
	v_exp_f32_e32 v76, v76
	v_exp_f32_e32 v77, v77
	s_waitcnt lgkmcnt(6)
	v_mfma_f32_16x16x32_bf16 v[196:199], v[22:25], v[112:115], v[192:195]
	v_mfma_f32_16x16x32_bf16 v[192:195], v[26:29], v[80:83], v[192:195]
	ds_read_b128 v[22:25], v253 offset:8896
	ds_read_b128 v[26:29], v253 offset:8768
	v_exp_f32_e32 v78, v78
	v_exp_f32_e32 v79, v79
	v_cvt_pk_bf16_f32 v0, v56, v57
	s_waitcnt lgkmcnt(6)
	v_mfma_f32_16x16x32_bf16 v[204:207], v[30:33], v[112:115], v[200:203]
	v_mfma_f32_16x16x32_bf16 v[200:203], v[34:37], v[80:83], v[200:203]
	ds_read_b128 v[30:33], v253 offset:13248
	ds_read_b128 v[34:37], v253 offset:13120
	v_cvt_pk_bf16_f32 v1, v58, v59
	v_cvt_pk_bf16_f32 v230, v72, v73
	v_cvt_pk_bf16_f32 v231, v74, v75
	s_waitcnt lgkmcnt(6)
	v_mfma_f32_16x16x32_bf16 v[156:159], v[6:9], v[128:131], v[156:159]
	v_mfma_f32_16x16x32_bf16 v[152:155], v[10:13], v[104:107], v[152:155]
	ds_read_b64 v[6:7], v246 offset:0
	ds_read_b64 v[8:9], v246 offset:32
	ds_read_b64 v[10:11], v246 offset:2304
	ds_read_b64 v[12:13], v246 offset:2336
	v_pk_add_f32 v[234:235], v[234:235], v[56:57]
	v_pk_add_f32 v[234:235], v[234:235], v[58:59]
	v_pk_add_f32 v[236:237], v[236:237], v[72:73]
	s_waitcnt lgkmcnt(8)
	v_mfma_f32_16x16x32_bf16 v[172:175], v[14:17], v[128:131], v[172:175]
	v_mfma_f32_16x16x32_bf16 v[168:171], v[18:21], v[104:107], v[168:171]
	ds_read_b64 v[14:15], v246 offset:4608
	ds_read_b64 v[16:17], v246 offset:4640
	ds_read_b64 v[18:19], v246 offset:6912
	ds_read_b64 v[20:21], v246 offset:6944
	v_pk_add_f32 v[236:237], v[236:237], v[74:75]
	v_cvt_pk_bf16_f32 v2, v60, v61
	v_cvt_pk_bf16_f32 v3, v62, v63
	s_waitcnt lgkmcnt(10)
	v_mfma_f32_16x16x32_bf16 v[196:199], v[22:25], v[128:131], v[196:199]
	v_mfma_f32_16x16x32_bf16 v[192:195], v[26:29], v[104:107], v[192:195]
	ds_read_b64 v[22:23], v246 offset:9216
	ds_read_b64 v[24:25], v246 offset:9248
	ds_read_b64 v[26:27], v246 offset:11520
	ds_read_b64 v[28:29], v246 offset:11552
	v_cvt_pk_bf16_f32 v232, v76, v77
	v_cvt_pk_bf16_f32 v233, v78, v79
	v_pk_add_f32 v[234:235], v[234:235], v[60:61]
	s_waitcnt lgkmcnt(12)
	v_mfma_f32_16x16x32_bf16 v[204:207], v[30:33], v[128:131], v[204:207]
	v_mfma_f32_16x16x32_bf16 v[200:203], v[34:37], v[104:107], v[200:203]
	ds_read_b64 v[30:31], v246 offset:13824
	ds_read_b64 v[32:33], v246 offset:13856
	ds_read_b64 v[34:35], v246 offset:16128
	ds_read_b64 v[36:37], v246 offset:16160
	v_pk_add_f32 v[234:235], v[234:235], v[62:63]
	v_pk_add_f32 v[236:237], v[236:237], v[76:77]
	v_pk_add_f32 v[236:237], v[236:237], v[78:79]
	s_add_i32 s5, s4, 2
	s_cmp_lt_u32 s5, s37
	s_cbranch_scc1 .Latt_lin_o
	s_cmp_le_u32 s5, s37
	s_cselect_b32 s45, s16, s18
	s_add_i32 s0, s37, 1
	s_cmp_le_u32 s5, s0
	s_cselect_b32 s43, s16, s18
	s_waitcnt lgkmcnt(12)
	v_mfma_f32_16x16x32_bf16 v[184:187], v[6:9], v[38:41], v[184:187]
	v_mfma_f32_16x16x32_bf16 v[188:191], v[6:9], v[42:45], v[188:191]
	v_mfma_f32_16x16x32_bf16 v[180:183], v[10:13], v[38:41], v[180:183]
	v_mfma_f32_16x16x32_bf16 v[176:179], v[10:13], v[42:45], v[176:179]
	ds_read_b64 v[6:7], v246 offset:64
	ds_read_b64 v[8:9], v246 offset:96
	ds_read_b64 v[10:11], v246 offset:2368
	ds_read_b64 v[12:13], v246 offset:2400
	v_mov_b32_e32 v4, s43
	v_fma_f32 v48, |v47|, s19, v4
	v_subrev_f32_e32 v49, 0x3f800000, v47
	v_fma_f32 v49, |v49|, s19, v4
	v_subrev_f32_e32 v50, 0x40000000, v47
	v_fma_f32 v50, |v50|, s19, v4
	v_subrev_f32_e32 v51, 0x40400000, v47
	v_fma_f32 v51, |v51|, s19, v4
	v_mov_b32_e32 v4, s45
	s_waitcnt lgkmcnt(12)
	v_mfma_f32_16x16x32_bf16 v[164:167], v[14:17], v[38:41], v[164:167]
	v_mfma_f32_16x16x32_bf16 v[160:163], v[14:17], v[42:45], v[160:163]
	v_mfma_f32_16x16x32_bf16 v[148:151], v[18:21], v[38:41], v[148:151]
	v_mfma_f32_16x16x32_bf16 v[144:147], v[18:21], v[42:45], v[144:147]
	ds_read_b64 v[14:15], v246 offset:4672
	ds_read_b64 v[16:17], v246 offset:4704
	ds_read_b64 v[18:19], v246 offset:6976
	ds_read_b64 v[20:21], v246 offset:7008
	v_subrev_f32_e32 v52, 0x41800000, v47
	v_fma_f32 v52, |v52|, s19, v4
	v_subrev_f32_e32 v53, 0x41880000, v47
	v_fma_f32 v53, |v53|, s19, v4
	v_subrev_f32_e32 v54, 0x41900000, v47
	v_fma_f32 v54, |v54|, s19, v4
	v_subrev_f32_e32 v55, 0x41980000, v47
	v_fma_f32 v55, |v55|, s19, v4
	v_subrev_f32_e32 v56, 0x42000000, v47
	s_waitcnt lgkmcnt(12)
	v_mfma_f32_16x16x32_bf16 v[140:143], v[22:25], v[38:41], v[140:143]
	v_mfma_f32_16x16x32_bf16 v[136:139], v[22:25], v[42:45], v[136:139]
	v_mfma_f32_16x16x32_bf16 v[132:135], v[26:29], v[38:41], v[132:135]
	v_mfma_f32_16x16x32_bf16 v[124:127], v[26:29], v[42:45], v[124:127]
	ds_read_b64 v[22:23], v246 offset:9280
	ds_read_b64 v[24:25], v246 offset:9312
	ds_read_b64 v[26:27], v246 offset:11584
	ds_read_b64 v[28:29], v246 offset:11616
	v_fma_f32 v56, |v56|, s19, v4
	v_subrev_f32_e32 v57, 0x42040000, v47
	v_fma_f32 v57, |v57|, s19, v4
	v_subrev_f32_e32 v58, 0x42080000, v47
	v_fma_f32 v58, |v58|, s19, v4
	v_subrev_f32_e32 v59, 0x420c0000, v47
	v_fma_f32 v59, |v59|, s19, v4
	v_subrev_f32_e32 v60, 0x42400000, v47
	s_waitcnt lgkmcnt(12)
	v_mfma_f32_16x16x32_bf16 v[120:123], v[30:33], v[38:41], v[120:123]
	v_mfma_f32_16x16x32_bf16 v[116:119], v[30:33], v[42:45], v[116:119]
	v_mfma_f32_16x16x32_bf16 v[108:111], v[34:37], v[38:41], v[108:111]
	v_mfma_f32_16x16x32_bf16 v[100:103], v[34:37], v[42:45], v[100:103]
	ds_read_b64 v[30:31], v246 offset:13888
	ds_read_b64 v[32:33], v246 offset:13920
	ds_read_b64 v[34:35], v246 offset:16192
	ds_read_b64 v[36:37], v246 offset:16224
	v_fma_f32 v60, |v60|, s19, v4
	v_subrev_f32_e32 v61, 0x42440000, v47
	v_fma_f32 v61, |v61|, s19, v4
	v_subrev_f32_e32 v62, 0x42480000, v47
	v_fma_f32 v62, |v62|, s19, v4
	v_subrev_f32_e32 v63, 0x424c0000, v47
	v_fma_f32 v63, |v63|, s19, v4
	v_add_f32_e32 v47, 0xc2800000, v47
	s_branch .Latt_c_o
; __device__ __forceinline__ void att_qk(const LAS unsigned char* Kb, const bf16x8 (&qf)[2][2], int nst, int j, int qpos, float slope2, int fr, int fq, f32x4 (&sc)[2][4]) {
;     constexpr int KSTR = 272;
; #pragma unroll
;     for (int st = 0; st < 4; ++st) {
;         if (st < nst) {
;             const float d0 = (float)(qpos - (64 * j + 16 * st + 4 * fq));
;             f32x4 s0;
; #pragma unroll
;             for (int e = 0; e < 4; ++e) s0[e] = -slope2 * __builtin_fabsf(d0 - (float)e) - 12.0f;
;             f32x4 s1 = s0;
; #pragma unroll
;             for (int ks = 0; ks < 2; ++ks) {
;                 const bf16x8 k0 = *(const LAS bf16x8*)(Kb + (16 * st + fr) * KSTR + (32 * ks + 8 * fq) * 2);
;                 const bf16x8 k1 = *(const LAS bf16x8*)(Kb + (16 * st + fr) * KSTR + (64 + 32 * ks + 8 * fq) * 2);
;                 s0 = __builtin_amdgcn_mfma_f32_16x16x32_bf16(k0, qf[0][ks], s0, 0, 0, 0);
;                 s1 = __builtin_amdgcn_mfma_f32_16x16x32_bf16(k1, qf[1][ks], s1, 0, 0, 0);
;             }
;             sc[0][st] = s0; sc[1][st] = s1;
;         }
;     }
; }
; __device__ __forceinline__ void att_pv(const LAS unsigned char* Vb, int nst, const f32x4 (&sc)[2][4], f32x4 (&O)[2][8], float& l0, float& l1, int fr, int fq) {
;     constexpr int VSTR = 144;
;     if (nst <= 0) return;
;     unsigned pw[2][4][2];
; #pragma unroll
;     for (int st = 0; st < 4; ++st) {
;         if (st < nst) {
;             float p0[4], p1[4];
; #pragma unroll
;             for (int e = 0; e < 4; ++e) { p0[e] = __builtin_amdgcn_exp2f(sc[0][st][e]); p1[e] = __builtin_amdgcn_exp2f(sc[1][st][e]); l0 += p0[e]; l1 += p1[e]; }
;             pw[0][st][0] = pk2(p0[0], p0[1]); pw[0][st][1] = pk2(p0[2], p0[3]); pw[1][st][0] = pk2(p1[0], p1[1]); pw[1][st][1] = pk2(p1[2], p1[3]);
;         } else { pw[0][st][0] = 0u; pw[0][st][1] = 0u; pw[1][st][0] = 0u; pw[1][st][1] = 0u; }
;     }
; #pragma unroll
;     for (int ks2 = 0; ks2 < 2; ++ks2) {
;         if (ks2 == 0 || nst == 4) {
;             const u32x4 a0 = (u32x4){pw[0][2 * ks2][0], pw[0][2 * ks2][1], pw[0][2 * ks2 + 1][0], pw[0][2 * ks2 + 1][1]};
;             const u32x4 a1 = (u32x4){pw[1][2 * ks2][0], pw[1][2 * ks2][1], pw[1][2 * ks2 + 1][0], pw[1][2 * ks2 + 1][1]};
;             const bf16x8 pf0 = __builtin_bit_cast(bf16x8, a0), pf1 = __builtin_bit_cast(bf16x8, a1);
; #pragma unroll
.Latt_lin_o:
	s_waitcnt lgkmcnt(12)
	v_mfma_f32_16x16x32_bf16 v[184:187], v[6:9], v[38:41], v[184:187]
	v_mfma_f32_16x16x32_bf16 v[188:191], v[6:9], v[42:45], v[188:191]
	v_mfma_f32_16x16x32_bf16 v[180:183], v[10:13], v[38:41], v[180:183]
	v_mfma_f32_16x16x32_bf16 v[176:179], v[10:13], v[42:45], v[176:179]
	ds_read_b64 v[6:7], v246 offset:64
	ds_read_b64 v[8:9], v246 offset:96
	ds_read_b64 v[10:11], v246 offset:2368
	ds_read_b64 v[12:13], v246 offset:2400
	v_mov_b32_e32 v4, s16
	v_fma_f32 v4, v47, s19, v4
	v_mov_b32_e32 v48, v4
	v_add_f32_e32 v49, s6, v4
	v_add_f32_e32 v50, s20, v4
	s_waitcnt lgkmcnt(12)
	v_mfma_f32_16x16x32_bf16 v[164:167], v[14:17], v[38:41], v[164:167]
	v_mfma_f32_16x16x32_bf16 v[160:163], v[14:17], v[42:45], v[160:163]
	v_mfma_f32_16x16x32_bf16 v[148:151], v[18:21], v[38:41], v[148:151]
	v_mfma_f32_16x16x32_bf16 v[144:147], v[18:21], v[42:45], v[144:147]
	ds_read_b64 v[14:15], v246 offset:4672
	ds_read_b64 v[16:17], v246 offset:4704
	ds_read_b64 v[18:19], v246 offset:6976
	ds_read_b64 v[20:21], v246 offset:7008
	v_add_f32_e32 v51, s21, v4
	v_add_f32_e32 v52, s35, v4
	v_add_f32_e32 v53, s38, v4
	v_add_f32_e32 v54, s39, v4
	v_add_f32_e32 v55, s40, v4
	s_waitcnt lgkmcnt(12)
	v_mfma_f32_16x16x32_bf16 v[140:143], v[22:25], v[38:41], v[140:143]
	v_mfma_f32_16x16x32_bf16 v[136:139], v[22:25], v[42:45], v[136:139]
	v_mfma_f32_16x16x32_bf16 v[132:135], v[26:29], v[38:41], v[132:135]
	v_mfma_f32_16x16x32_bf16 v[124:127], v[26:29], v[42:45], v[124:127]
	ds_read_b64 v[22:23], v246 offset:9280
	ds_read_b64 v[24:25], v246 offset:9312
	ds_read_b64 v[26:27], v246 offset:11584
	ds_read_b64 v[28:29], v246 offset:11616
	v_add_f32_e32 v56, s41, v4
	v_add_f32_e32 v57, s42, v4
	v_add_f32_e32 v58, s48, v4
	v_add_f32_e32 v59, s49, v4
	v_add_f32_e32 v60, s98, v4
	s_waitcnt lgkmcnt(12)
	v_mfma_f32_16x16x32_bf16 v[120:123], v[30:33], v[38:41], v[120:123]
	v_mfma_f32_16x16x32_bf16 v[116:119], v[30:33], v[42:45], v[116:119]
	v_mfma_f32_16x16x32_bf16 v[108:111], v[34:37], v[38:41], v[108:111]
	v_mfma_f32_16x16x32_bf16 v[100:103], v[34:37], v[42:45], v[100:103]
	ds_read_b64 v[30:31], v246 offset:13888
	ds_read_b64 v[32:33], v246 offset:13920
	ds_read_b64 v[34:35], v246 offset:16192
	ds_read_b64 v[36:37], v246 offset:16224
	v_add_f32_e32 v61, s99, v4
	v_add_f32_e32 v62, s100, v4
	v_add_f32_e32 v63, s101, v4
	v_add_f32_e32 v47, 0xc2800000, v47
.Latt_c_o:
	s_waitcnt vmcnt(0)
	ds_write_b128 v251, v[84:87] offset:17408
	ds_write_b128 v251, v[88:91] offset:17536
	ds_write_b128 v252, v[92:95] offset:34816
	ds_write_b128 v252, v[96:99] offset:34880
	s_sub_i32 s1, s36, 1
	s_add_i32 s0, s4, 3
	s_min_u32 s0, s0, s1
	s_add_i32 s5, s4, 2
	s_min_u32 s5, s5, s1
	s_lshl_b32 s0, s0, 6
	s_lshl_b32 s5, s5, 7
	v_add_u32_e32 v223, s0, v243
	v_min_u32_e32 v223, 0x7ff, v223
	v_lshl_add_u32 v223, v223, 10, v224
	s_add_u32 s26, s24, s5
	s_addc_u32 s27, s25, 0
	global_load_dwordx4 v[84:87], v223, s[22:23]
	global_load_dwordx4 v[88:91], v223, s[22:23] offset:128
	global_load_dwordx4 v[92:95], v46, s[26:27]
	global_load_dwordx4 v[96:99], v46, s[26:27] offset:64
	s_waitcnt lgkmcnt(15)
	v_mfma_f32_16x16x32_bf16 v[184:187], v[6:9], v[0:3], v[184:187]
	v_mfma_f32_16x16x32_bf16 v[188:191], v[6:9], v[230:233], v[188:191]
	v_mfma_f32_16x16x32_bf16 v[180:183], v[10:13], v[0:3], v[180:183]
	v_mfma_f32_16x16x32_bf16 v[176:179], v[10:13], v[230:233], v[176:179]
	v_exp_f32_e32 v152, v152
	v_exp_f32_e32 v153, v153
	v_exp_f32_e32 v154, v154
	v_exp_f32_e32 v155, v155
	v_exp_f32_e32 v156, v156
	v_exp_f32_e32 v157, v157
	v_exp_f32_e32 v158, v158
	v_exp_f32_e32 v159, v159
	s_waitcnt lgkmcnt(12)
	v_mfma_f32_16x16x32_bf16 v[164:167], v[14:17], v[0:3], v[164:167]
	v_mfma_f32_16x16x32_bf16 v[160:163], v[14:17], v[230:233], v[160:163]
	v_mfma_f32_16x16x32_bf16 v[148:151], v[18:21], v[0:3], v[148:151]
	v_mfma_f32_16x16x32_bf16 v[144:147], v[18:21], v[230:233], v[144:147]
	v_exp_f32_e32 v168, v168
	v_exp_f32_e32 v169, v169
	v_exp_f32_e32 v170, v170
	v_exp_f32_e32 v171, v171
	v_exp_f32_e32 v172, v172
	v_exp_f32_e32 v173, v173
	v_exp_f32_e32 v174, v174
	v_exp_f32_e32 v175, v175
	s_waitcnt lgkmcnt(8)
	v_mfma_f32_16x16x32_bf16 v[140:143], v[22:25], v[0:3], v[140:143]
	v_mfma_f32_16x16x32_bf16 v[136:139], v[22:25], v[230:233], v[136:139]
	v_mfma_f32_16x16x32_bf16 v[132:135], v[26:29], v[0:3], v[132:135]
	v_mfma_f32_16x16x32_bf16 v[124:127], v[26:29], v[230:233], v[124:127]
	v_cvt_pk_bf16_f32 v38, v152, v153
	v_cvt_pk_bf16_f32 v39, v154, v155
	v_cvt_pk_bf16_f32 v42, v156, v157
	v_cvt_pk_bf16_f32 v43, v158, v159
	v_pk_add_f32 v[234:235], v[234:235], v[152:153]
	v_pk_add_f32 v[234:235], v[234:235], v[154:155]
	v_pk_add_f32 v[236:237], v[236:237], v[156:157]
	v_pk_add_f32 v[236:237], v[236:237], v[158:159]
	s_waitcnt lgkmcnt(4)
	v_mfma_f32_16x16x32_bf16 v[120:123], v[30:33], v[0:3], v[120:123]
	v_mfma_f32_16x16x32_bf16 v[116:119], v[30:33], v[230:233], v[116:119]
	v_mfma_f32_16x16x32_bf16 v[108:111], v[34:37], v[0:3], v[108:111]
	v_mfma_f32_16x16x32_bf16 v[100:103], v[34:37], v[230:233], v[100:103]
	v_cvt_pk_bf16_f32 v40, v168, v169
	v_cvt_pk_bf16_f32 v41, v170, v171
	v_cvt_pk_bf16_f32 v44, v172, v173
	v_cvt_pk_bf16_f32 v45, v174, v175
	v_pk_add_f32 v[234:235], v[234:235], v[168:169]
	v_pk_add_f32 v[234:235], v[234:235], v[170:171]
	v_pk_add_f32 v[236:237], v[236:237], v[172:173]
	v_pk_add_f32 v[236:237], v[236:237], v[174:175]
	s_waitcnt lgkmcnt(0)
	s_barrier
	s_add_i32 s4, s4, 1
	s_branch .Latt_top
; #define LAS __attribute__((address_space(3)))
; __device__ __forceinline__ unsigned pk2(float lo, float hi) { return pg8::cvt_pk_bf16(lo, hi); }
; __device__ __forceinline__ void att_pv(const LAS unsigned char* Vb, int nst, const f32x4 (&sc)[2][4], f32x4 (&O)[2][8], float& l0, float& l1, int fr, int fq) {
;     constexpr int VSTR = 144;
;     if (nst <= 0) return;
;     unsigned pw[2][4][2];
; #pragma unroll
;     for (int st = 0; st < 4; ++st) {
;         if (st < nst) {
;             float p0[4], p1[4];
; #pragma unroll
;             for (int e = 0; e < 4; ++e) { p0[e] = __builtin_amdgcn_exp2f(sc[0][st][e]); p1[e] = __builtin_amdgcn_exp2f(sc[1][st][e]); l0 += p0[e]; l1 += p1[e]; }
;             pw[0][st][0] = pk2(p0[0], p0[1]); pw[0][st][1] = pk2(p0[2], p0[3]); pw[1][st][0] = pk2(p1[0], p1[1]); pw[1][st][1] = pk2(p1[2], p1[3]);
;         } else { pw[0][st][0] = 0u; pw[0][st][1] = 0u; pw[1][st][0] = 0u; pw[1][st][1] = 0u; }
;     }
; #pragma unroll
;     for (int ks2 = 0; ks2 < 2; ++ks2) {
;         if (ks2 == 0 || nst == 4) {
;             const u32x4 a0 = (u32x4){pw[0][2 * ks2][0], pw[0][2 * ks2][1], pw[0][2 * ks2 + 1][0], pw[0][2 * ks2 + 1][1]};
;             const u32x4 a1 = (u32x4){pw[1][2 * ks2][0], pw[1][2 * ks2][1], pw[1][2 * ks2 + 1][0], pw[1][2 * ks2 + 1][1]};
;             const bf16x8 pf0 = __builtin_bit_cast(bf16x8, a0), pf1 = __builtin_bit_cast(bf16x8, a1);
; #pragma unroll
;             for (int dt = 0; dt < 8; ++dt) {
;                 const LAS unsigned char* vp = Vb + (16 * dt + fr) * VSTR + (32 * ks2 + 4 * fq) * 2;
;                 const u32x2 va = *(const LAS u32x2*)vp, vb2 = *(const LAS u32x2*)(vp + 32);
;                 const bf16x8 vf = __builtin_bit_cast(bf16x8, (u32x4){va.x, va.y, vb2.x, vb2.y});
;                 O[0][dt] = __builtin_amdgcn_mfma_f32_16x16x32_bf16(vf, pf0, O[0][dt], 0, 0, 0);
;                 O[1][dt] = __builtin_amdgcn_mfma_f32_16x16x32_bf16(vf, pf1, O[1][dt], 0, 0, 0);
;             }
;         }
;     }
; }
; __device__ __forceinline__ void attn_phase(const Params& P, LAS unsigned char* lds, int tid, int wid, int lane) {
;     ...
;             att_pv(lds + VOFF, ATT_NST(j), scA, O, l0, l1, fr, fq);
;             if (j + 1 < nt) { if (j + 2 < nt) ATT_WRITEK(a, 0); ATT_WRITEV(a, 1); }
;             ATT_BAR();
;             if (j + 1 >= nt) break;
.Latt_it_l:
	ds_read_b64 v[6:7], v245 offset:34816
	ds_read_b64 v[8:9], v245 offset:34848
	ds_read_b64 v[10:11], v245 offset:37120
	ds_read_b64 v[12:13], v245 offset:37152
	ds_read_b64 v[14:15], v245 offset:39424
	ds_read_b64 v[16:17], v245 offset:39456
	ds_read_b64 v[18:19], v245 offset:41728
	ds_read_b64 v[20:21], v245 offset:41760
	ds_read_b64 v[22:23], v245 offset:44032
	ds_read_b64 v[24:25], v245 offset:44064
	ds_read_b64 v[26:27], v245 offset:46336
	ds_read_b64 v[28:29], v245 offset:46368
	ds_read_b64 v[30:31], v245 offset:48640
	ds_read_b64 v[32:33], v245 offset:48672
	ds_read_b64 v[34:35], v245 offset:50944
	ds_read_b64 v[36:37], v245 offset:50976
	s_waitcnt lgkmcnt(12)
	v_mfma_f32_16x16x32_bf16 v[184:187], v[6:9], v[38:41], v[184:187]
	v_mfma_f32_16x16x32_bf16 v[188:191], v[6:9], v[42:45], v[188:191]
	v_mfma_f32_16x16x32_bf16 v[180:183], v[10:13], v[38:41], v[180:183]
	v_mfma_f32_16x16x32_bf16 v[176:179], v[10:13], v[42:45], v[176:179]
	ds_read_b64 v[6:7], v245 offset:34880
	ds_read_b64 v[8:9], v245 offset:34912
	ds_read_b64 v[10:11], v245 offset:37184
	ds_read_b64 v[12:13], v245 offset:37216
	v_exp_f32_e32 v192, v192
	v_exp_f32_e32 v193, v193
	v_exp_f32_e32 v194, v194
	v_exp_f32_e32 v195, v195
	v_exp_f32_e32 v196, v196
	v_exp_f32_e32 v197, v197
	v_exp_f32_e32 v198, v198
	v_exp_f32_e32 v199, v199
	s_waitcnt lgkmcnt(12)
	v_mfma_f32_16x16x32_bf16 v[164:167], v[14:17], v[38:41], v[164:167]
	v_mfma_f32_16x16x32_bf16 v[160:163], v[14:17], v[42:45], v[160:163]
	v_mfma_f32_16x16x32_bf16 v[148:151], v[18:21], v[38:41], v[148:151]
	v_mfma_f32_16x16x32_bf16 v[144:147], v[18:21], v[42:45], v[144:147]
	ds_read_b64 v[14:15], v245 offset:39488
	ds_read_b64 v[16:17], v245 offset:39520
	ds_read_b64 v[18:19], v245 offset:41792
	ds_read_b64 v[20:21], v245 offset:41824
	v_exp_f32_e32 v200, v200
	v_exp_f32_e32 v201, v201
	v_exp_f32_e32 v202, v202
	v_exp_f32_e32 v203, v203
	v_exp_f32_e32 v204, v204
	v_exp_f32_e32 v205, v205
	v_exp_f32_e32 v206, v206
	v_exp_f32_e32 v207, v207
	s_waitcnt lgkmcnt(12)
	v_mfma_f32_16x16x32_bf16 v[140:143], v[22:25], v[38:41], v[140:143]
	v_mfma_f32_16x16x32_bf16 v[136:139], v[22:25], v[42:45], v[136:139]
	v_mfma_f32_16x16x32_bf16 v[132:135], v[26:29], v[38:41], v[132:135]
	v_mfma_f32_16x16x32_bf16 v[124:127], v[26:29], v[42:45], v[124:127]
	ds_read_b64 v[22:23], v245 offset:44096
	ds_read_b64 v[24:25], v245 offset:44128
	ds_read_b64 v[26:27], v245 offset:46400
	ds_read_b64 v[28:29], v245 offset:46432
	v_cvt_pk_bf16_f32 v0, v192, v193
	v_cvt_pk_bf16_f32 v1, v194, v195
	v_cvt_pk_bf16_f32 v230, v196, v197
	v_cvt_pk_bf16_f32 v231, v198, v199
	v_pk_add_f32 v[234:235], v[234:235], v[192:193]
	v_pk_add_f32 v[234:235], v[234:235], v[194:195]
	v_pk_add_f32 v[236:237], v[236:237], v[196:197]
	v_pk_add_f32 v[236:237], v[236:237], v[198:199]
	s_waitcnt lgkmcnt(12)
	v_mfma_f32_16x16x32_bf16 v[120:123], v[30:33], v[38:41], v[120:123]
	v_mfma_f32_16x16x32_bf16 v[116:119], v[30:33], v[42:45], v[116:119]
	v_mfma_f32_16x16x32_bf16 v[108:111], v[34:37], v[38:41], v[108:111]
	v_mfma_f32_16x16x32_bf16 v[100:103], v[34:37], v[42:45], v[100:103]
	ds_read_b64 v[30:31], v245 offset:48704
	ds_read_b64 v[32:33], v245 offset:48736
	ds_read_b64 v[34:35], v245 offset:51008
	ds_read_b64 v[36:37], v245 offset:51040
	v_cvt_pk_bf16_f32 v2, v200, v201
	v_cvt_pk_bf16_f32 v3, v202, v203
	v_cvt_pk_bf16_f32 v232, v204, v205
	v_cvt_pk_bf16_f32 v233, v206, v207
	v_pk_add_f32 v[234:235], v[234:235], v[200:201]
	v_pk_add_f32 v[234:235], v[234:235], v[202:203]
	v_pk_add_f32 v[236:237], v[236:237], v[204:205]
	v_pk_add_f32 v[236:237], v[236:237], v[206:207]
	s_waitcnt lgkmcnt(12)
	v_mfma_f32_16x16x32_bf16 v[184:187], v[6:9], v[0:3], v[184:187]
	v_mfma_f32_16x16x32_bf16 v[188:191], v[6:9], v[230:233], v[188:191]
	v_mfma_f32_16x16x32_bf16 v[180:183], v[10:13], v[0:3], v[180:183]
	v_mfma_f32_16x16x32_bf16 v[176:179], v[10:13], v[230:233], v[176:179]
	s_waitcnt lgkmcnt(8)
	v_mfma_f32_16x16x32_bf16 v[164:167], v[14:17], v[0:3], v[164:167]
	v_mfma_f32_16x16x32_bf16 v[160:163], v[14:17], v[230:233], v[160:163]
	v_mfma_f32_16x16x32_bf16 v[148:151], v[18:21], v[0:3], v[148:151]
	v_mfma_f32_16x16x32_bf16 v[144:147], v[18:21], v[230:233], v[144:147]
	s_waitcnt lgkmcnt(4)
	v_mfma_f32_16x16x32_bf16 v[140:143], v[22:25], v[0:3], v[140:143]
	v_mfma_f32_16x16x32_bf16 v[136:139], v[22:25], v[230:233], v[136:139]
	v_mfma_f32_16x16x32_bf16 v[132:135], v[26:29], v[0:3], v[132:135]
	v_mfma_f32_16x16x32_bf16 v[124:127], v[26:29], v[230:233], v[124:127]
	s_waitcnt lgkmcnt(0)
	v_mfma_f32_16x16x32_bf16 v[120:123], v[30:33], v[0:3], v[120:123]
	v_mfma_f32_16x16x32_bf16 v[116:119], v[30:33], v[230:233], v[116:119]
	v_mfma_f32_16x16x32_bf16 v[108:111], v[34:37], v[0:3], v[108:111]
	v_mfma_f32_16x16x32_bf16 v[100:103], v[34:37], v[230:233], v[100:103]

; #define LAS __attribute__((address_space(3)))
; __global__ void __launch_bounds__(NTHREADS, 2) mega(Params P, int ph_lo, int ph_hi) {
;     extern __shared__ __attribute__((aligned(16))) unsigned char lds_raw[];
;     LAS unsigned char* lds = (LAS unsigned char*)lds_raw;
;     cg::grid_group grid = cg::this_grid();
;     const int tid = threadIdx.x, lane = tid & 63, wid = __builtin_amdgcn_readfirstlane(tid >> 6);
;     const int G = gridDim.x, gw = blockIdx.x * NWAVES + wid, NGW = G * NWAVES;
	.amdhsa_kernel _Z4mega6Paramsii
		.amdhsa_group_segment_fixed_size 0
		.amdhsa_private_segment_fixed_size 0
		.amdhsa_kernarg_size 504
		.amdhsa_user_sgpr_count 2
		.amdhsa_user_sgpr_dispatch_ptr 0
		.amdhsa_user_sgpr_queue_ptr 0
		.amdhsa_user_sgpr_kernarg_segment_ptr 1
		.amdhsa_user_sgpr_dispatch_id 0
		.amdhsa_user_sgpr_kernarg_preload_length 0
		.amdhsa_user_sgpr_kernarg_preload_offset 0
		.amdhsa_user_sgpr_private_segment_size 0
		.amdhsa_uses_dynamic_stack 0
		.amdhsa_enable_private_segment 0
		.amdhsa_system_sgpr_workgroup_id_x 1
		.amdhsa_system_sgpr_workgroup_id_y 0
		.amdhsa_system_sgpr_workgroup_id_z 0
		.amdhsa_system_sgpr_workgroup_info 0
		.amdhsa_system_vgpr_workitem_id 2
		.amdhsa_next_free_vgpr 255
		.amdhsa_next_free_sgpr 102
		.amdhsa_accum_offset 256
		.amdhsa_reserve_vcc 1
		.amdhsa_float_round_mode_32 0
		.amdhsa_float_round_mode_16_64 0
		.amdhsa_float_denorm_mode_32 3
		.amdhsa_float_denorm_mode_16_64 3
		.amdhsa_dx10_clamp 1
		.amdhsa_ieee_mode 1
		.amdhsa_fp16_overflow 0
		.amdhsa_tg_split 0
		.amdhsa_exception_fp_ieee_invalid_op 0
		.amdhsa_exception_fp_denorm_src 0
		.amdhsa_exception_fp_ieee_div_zero 0
		.amdhsa_exception_fp_ieee_overflow 0
		.amdhsa_exception_fp_ieee_underflow 0
		.amdhsa_exception_fp_ieee_inexact 0
		.amdhsa_exception_int_div_zero 0
	.end_amdhsa_kernel

; #define LAS __attribute__((address_space(3)))
; __global__ void __launch_bounds__(NTHREADS, 2) mega(Params P, int ph_lo, int ph_hi) {
;     extern __shared__ __attribute__((aligned(16))) unsigned char lds_raw[];
;     LAS unsigned char* lds = (LAS unsigned char*)lds_raw;
;     cg::grid_group grid = cg::this_grid();
;     const int tid = threadIdx.x, lane = tid & 63, wid = __builtin_amdgcn_readfirstlane(tid >> 6);
;     const int G = gridDim.x, gw = blockIdx.x * NWAVES + wid, NGW = G * NWAVES;
amdhsa.kernels:
  - .agpr_count:     0
    .args:
      - .offset:         0
        .size:           240
        .value_kind:     by_value
      - .offset:         240
        .size:           4
        .value_kind:     by_value
      - .offset:         244
        .size:           4
        .value_kind:     by_value
      - .offset:         248
        .size:           4
        .value_kind:     hidden_block_count_x
      - .offset:         252
        .size:           4
        .value_kind:     hidden_block_count_y
      - .offset:         256
        .size:           4
        .value_kind:     hidden_block_count_z
      - .offset:         260
        .size:           2
        .value_kind:     hidden_group_size_x
      - .offset:         262
        .size:           2
        .value_kind:     hidden_group_size_y
      - .offset:         264
        .size:           2
        .value_kind:     hidden_group_size_z
      - .offset:         266
        .size:           2
        .value_kind:     hidden_remainder_x
      - .offset:         268
        .size:           2
        .value_kind:     hidden_remainder_y
      - .offset:         270
        .size:           2
        .value_kind:     hidden_remainder_z
      - .offset:         288
        .size:           8
        .value_kind:     hidden_global_offset_x
      - .offset:         296
        .size:           8
        .value_kind:     hidden_global_offset_y
      - .offset:         304
        .size:           8
        .value_kind:     hidden_global_offset_z
      - .offset:         312
        .size:           2
        .value_kind:     hidden_grid_dims
      - .offset:         336
        .size:           8
        .value_kind:     hidden_multigrid_sync_arg
      - .offset:         368
        .size:           4
        .value_kind:     hidden_dynamic_lds_size
    .group_segment_fixed_size: 0
    .kernarg_segment_align: 8
    .kernarg_segment_size: 504
    .language:       OpenCL C
    .language_version:
      - 2
      - 0
    .max_flat_workgroup_size: 512
    .name:           _Z4mega6Paramsii
    .private_segment_fixed_size: 0
    .sgpr_count:     108
    .sgpr_spill_count: 42
    .symbol:         _Z4mega6Paramsii.kd
    .uniform_work_group_size: 1
    .uses_dynamic_stack: false
    .vgpr_count:     255
    .vgpr_spill_count: 0
    .wavefront_size: 64
